# attention tile bodies: diagonal-mask and running-max paths moved out of line, common path falls through
# speedup vs baseline: 1.0061x; 1.0061x over previous
.LBB0_532:
	s_add_i32 s60, s84, s83
	s_add_i32 s56, s60, 0x7c0
	s_cmp_gt_i32 s56, s79
	s_cbranch_scc1 .LBB0_541
	v_add_u32_e32 v16, v206, v205
	ds_read_b128 v[4:7], v16
	ds_read_b128 v[8:11], v16 offset:32
	v_add3_u32 v2, s84, v220, 64
	v_cvt_f32_i32_e32 v2, v2
	s_andn2_b64 vcc, exec, s[58:59]
	v_fma_f32 v2, v190, v2, -v185
	v_fma_f32 v82, 0, v190, v2
	v_add_f32_e32 v83, v190, v2
	v_fma_f32 v84, v190, s16, v2
	v_fma_f32 v85, v191, s17, v2
	v_fma_f32 v86, v190, s18, v2
	v_fma_f32 v87, v191, s19, v2
	v_fma_f32 v88, v190, s20, v2
	v_fma_f32 v89, v191, s21, v2
	v_fma_f32 v90, v190, s22, v2
	v_fma_f32 v91, v191, s23, v2
	v_fma_f32 v92, v190, s24, v2
	v_fma_f32 v93, v191, s25, v2
	v_fma_f32 v94, v190, s36, v2
	v_fma_f32 v95, v191, s37, v2
	v_fma_f32 v96, v190, s54, v2
	v_fma_f32 v97, v191, s55, v2
	v_add_f32_e32 v2, v219, v2
	v_fma_f32 v98, 0, v190, v2
	s_waitcnt lgkmcnt(1)
	v_mfma_f32_32x32x16_bf16 v[82:97], v[4:7], v[114:117], v[82:97]
	v_add_f32_e32 v99, v190, v2
	v_fma_f32 v100, v190, s16, v2
	v_fma_f32 v101, v191, s17, v2
	v_fma_f32 v102, v190, s18, v2
	v_fma_f32 v103, v191, s19, v2
	v_fma_f32 v104, v190, s20, v2
	v_fma_f32 v105, v191, s21, v2
	v_fma_f32 v106, v190, s22, v2
	v_fma_f32 v107, v191, s23, v2
	v_fma_f32 v108, v190, s24, v2
	v_fma_f32 v109, v191, s25, v2
	v_fma_f32 v110, v190, s36, v2
	v_fma_f32 v111, v191, s37, v2
	s_waitcnt lgkmcnt(0)
	v_mfma_f32_32x32x16_bf16 v[82:97], v[8:11], v[118:121], v[82:97]
	ds_read_b128 v[4:7], v16 offset:64
	ds_read_b128 v[8:11], v16 offset:96
	v_fma_f32 v112, v190, s54, v2
	v_fma_f32 v113, v191, s55, v2
	s_waitcnt lgkmcnt(1)
	v_mfma_f32_32x32x16_bf16 v[82:97], v[4:7], v[122:125], v[82:97]
	ds_read_b128 v[4:7], v16 offset:8704
	ds_read_b128 v[12:15], v16 offset:8736
	s_waitcnt lgkmcnt(1)
	v_mfma_f32_32x32x16_bf16 v[98:113], v[4:7], v[114:117], v[98:113]
	s_waitcnt lgkmcnt(0)
	v_mfma_f32_32x32x16_bf16 v[98:113], v[12:15], v[118:121], v[98:113]
	v_mfma_f32_32x32x16_bf16 v[82:97], v[8:11], v[126:129], v[82:97]
	ds_read_b128 v[4:7], v16 offset:8768
	ds_read_b128 v[224:227], v16 offset:8800
	ds_read_b64_tr_b16 v[12:13], v207 offset:17408
	ds_read_b64_tr_b16 v[14:15], v207 offset:19968
	ds_read_b64_tr_b16 v[8:9], v207 offset:17472
	ds_read_b64_tr_b16 v[10:11], v207 offset:20032
	s_waitcnt lgkmcnt(5)
	v_mfma_f32_32x32x16_bf16 v[98:113], v[4:7], v[122:125], v[98:113]
	ds_read_b64_tr_b16 v[162:163], v207 offset:17536
	ds_read_b64_tr_b16 v[164:165], v207 offset:20096
	ds_read_b64_tr_b16 v[4:5], v207 offset:17600
	ds_read_b64_tr_b16 v[6:7], v207 offset:20160
	s_waitcnt lgkmcnt(8)
	v_mfma_f32_32x32x16_bf16 v[98:113], v[224:227], v[126:129], v[98:113]
	s_cbranch_vccz .Lmy_maskA
.LBB0_535:
	s_andn2_b64 vcc, exec, s[4:5]
	s_cbranch_vccz .Lmy_nfA

.LBB0_549:
	v_add_u32_e32 v16, v206, v205
	ds_read_b128 v[4:7], v16 offset:37888
	ds_read_b128 v[8:11], v16 offset:37920
	v_add_u32_e32 v2, s84, v220
	v_cvt_f32_i32_e32 v2, v2
	s_andn2_b64 vcc, exec, s[58:59]
	v_fma_f32 v2, v190, v2, -v185
	v_fma_f32 v82, 0, v190, v2
	v_add_f32_e32 v83, v190, v2
	v_fma_f32 v84, v190, s16, v2
	v_fma_f32 v85, v191, s17, v2
	v_fma_f32 v86, v190, s18, v2
	v_fma_f32 v87, v191, s19, v2
	v_fma_f32 v88, v190, s20, v2
	v_fma_f32 v89, v191, s21, v2
	v_fma_f32 v90, v190, s22, v2
	v_fma_f32 v91, v191, s23, v2
	v_fma_f32 v92, v190, s24, v2
	v_fma_f32 v93, v191, s25, v2
	v_fma_f32 v94, v190, s36, v2
	v_fma_f32 v95, v191, s37, v2
	v_fma_f32 v96, v190, s54, v2
	v_fma_f32 v97, v191, s55, v2
	v_add_f32_e32 v2, v219, v2
	v_fma_f32 v98, 0, v190, v2
	s_waitcnt lgkmcnt(1)
	v_mfma_f32_32x32x16_bf16 v[82:97], v[4:7], v[114:117], v[82:97]
	v_add_f32_e32 v99, v190, v2
	v_fma_f32 v100, v190, s16, v2
	v_fma_f32 v101, v191, s17, v2
	v_fma_f32 v102, v190, s18, v2
	v_fma_f32 v103, v191, s19, v2
	v_fma_f32 v104, v190, s20, v2
	v_fma_f32 v105, v191, s21, v2
	v_fma_f32 v106, v190, s22, v2
	v_fma_f32 v107, v191, s23, v2
	v_fma_f32 v108, v190, s24, v2
	v_fma_f32 v109, v191, s25, v2
	v_fma_f32 v110, v190, s36, v2
	v_fma_f32 v111, v191, s37, v2
	s_waitcnt lgkmcnt(0)
	v_mfma_f32_32x32x16_bf16 v[82:97], v[8:11], v[118:121], v[82:97]
	ds_read_b128 v[4:7], v16 offset:37952
	ds_read_b128 v[8:11], v16 offset:37984
	v_fma_f32 v112, v190, s54, v2
	v_fma_f32 v113, v191, s55, v2
	s_waitcnt lgkmcnt(1)
	v_mfma_f32_32x32x16_bf16 v[82:97], v[4:7], v[122:125], v[82:97]
	ds_read_b128 v[4:7], v16 offset:46592
	ds_read_b128 v[12:15], v16 offset:46624
	s_waitcnt lgkmcnt(1)
	v_mfma_f32_32x32x16_bf16 v[98:113], v[4:7], v[114:117], v[98:113]
	s_waitcnt lgkmcnt(0)
	v_mfma_f32_32x32x16_bf16 v[98:113], v[12:15], v[118:121], v[98:113]
	ds_read_b128 v[4:7], v16 offset:46656
	ds_read_b128 v[224:227], v16 offset:46688
	ds_read_b64_tr_b16 v[162:163], v210 offset:0
	ds_read_b64_tr_b16 v[164:165], v210 offset:2560
	ds_read_b64_tr_b16 v[12:13], v210 offset:64
	ds_read_b64_tr_b16 v[14:15], v210 offset:2624
	s_waitcnt lgkmcnt(5)
	v_mfma_f32_32x32x16_bf16 v[98:113], v[4:7], v[122:125], v[98:113]
	v_mfma_f32_32x32x16_bf16 v[82:97], v[8:11], v[126:129], v[82:97]
	ds_read_b64_tr_b16 v[8:9], v210 offset:128
	ds_read_b64_tr_b16 v[10:11], v210 offset:2688
	ds_read_b64_tr_b16 v[4:5], v210 offset:192
	ds_read_b64_tr_b16 v[6:7], v210 offset:2752
	s_waitcnt lgkmcnt(8)
	v_mfma_f32_32x32x16_bf16 v[98:113], v[224:227], v[126:129], v[98:113]
	s_cbranch_vccz .Lmy_maskB

.Lmy_maskA:
	v_add_u32_e32 v2, s84, v222
	v_add_u32_e32 v17, 0x7e0, v2
	v_add_u32_e32 v16, 0x7c0, v2
	v_cmp_le_i32_e32 vcc, v17, v184
	s_nop 6
	v_cndmask_b32_e32 v98, v217, v98, vcc
	v_cmp_lt_i32_e32 vcc, v16, v184
	s_nop 1
	v_cndmask_b32_e32 v83, v217, v83, vcc
	v_cmp_le_i32_e32 vcc, v16, v184
	v_add_u32_e32 v16, 0x7e1, v2
	s_nop 0
	v_cndmask_b32_e32 v82, v217, v82, vcc
	v_cmp_le_i32_e32 vcc, v16, v184
	v_add_u32_e32 v16, 0x7c2, v2
	s_nop 0
	v_cndmask_b32_e32 v99, v217, v99, vcc
	v_cmp_le_i32_e32 vcc, v16, v184
	v_add_u32_e32 v16, 0x7e2, v2
	s_nop 0
	v_cndmask_b32_e32 v84, v217, v84, vcc
	v_cmp_le_i32_e32 vcc, v16, v184
	v_add_u32_e32 v16, 0x7c3, v2
	s_nop 0
	v_cndmask_b32_e32 v100, v217, v100, vcc
	v_cmp_le_i32_e32 vcc, v16, v184
	v_add_u32_e32 v16, 0x7e3, v2
	s_nop 0
	v_cndmask_b32_e32 v85, v217, v85, vcc
	v_cmp_le_i32_e32 vcc, v16, v184
	v_add_u32_e32 v16, 0x7c8, v2
	s_nop 0
	v_cndmask_b32_e32 v101, v217, v101, vcc
	v_cmp_le_i32_e32 vcc, v16, v184
	v_add_u32_e32 v16, 0x7e8, v2
	s_nop 0
	v_cndmask_b32_e32 v86, v217, v86, vcc
	v_cmp_le_i32_e32 vcc, v16, v184
	v_add_u32_e32 v16, 0x7c9, v2
	s_nop 0
	v_cndmask_b32_e32 v102, v217, v102, vcc
	v_cmp_le_i32_e32 vcc, v16, v184
	v_add_u32_e32 v16, 0x7e9, v2
	s_nop 0
	v_cndmask_b32_e32 v87, v217, v87, vcc
	v_cmp_le_i32_e32 vcc, v16, v184
	v_add_u32_e32 v16, 0x7ca, v2
	s_nop 0
	v_cndmask_b32_e32 v103, v217, v103, vcc
	v_cmp_le_i32_e32 vcc, v16, v184
	v_add_u32_e32 v16, 0x7ea, v2
	s_nop 0
	v_cndmask_b32_e32 v88, v217, v88, vcc
	v_cmp_le_i32_e32 vcc, v16, v184
	v_add_u32_e32 v16, 0x7cb, v2
	s_nop 0
	v_cndmask_b32_e32 v104, v217, v104, vcc
	v_cmp_le_i32_e32 vcc, v16, v184
	v_add_u32_e32 v16, 0x7eb, v2
	s_nop 0
	v_cndmask_b32_e32 v89, v217, v89, vcc
	v_cmp_le_i32_e32 vcc, v16, v184
	v_add_u32_e32 v16, 0x7d0, v2
	s_nop 0
	v_cndmask_b32_e32 v105, v217, v105, vcc
	v_cmp_le_i32_e32 vcc, v16, v184
	v_add_u32_e32 v16, 0x7f0, v2
	s_nop 0
	v_cndmask_b32_e32 v90, v217, v90, vcc
	v_cmp_le_i32_e32 vcc, v16, v184
	v_add_u32_e32 v16, 0x7d1, v2
	s_nop 0
	v_cndmask_b32_e32 v106, v217, v106, vcc
	v_cmp_le_i32_e32 vcc, v16, v184
	v_add_u32_e32 v16, 0x7f1, v2
	s_nop 0
	v_cndmask_b32_e32 v91, v217, v91, vcc
	v_cmp_le_i32_e32 vcc, v16, v184
	v_add_u32_e32 v16, 0x7d2, v2
	s_nop 0
	v_cndmask_b32_e32 v107, v217, v107, vcc
	v_cmp_le_i32_e32 vcc, v16, v184
	v_add_u32_e32 v16, 0x7f2, v2
	s_nop 0
	v_cndmask_b32_e32 v92, v217, v92, vcc
	v_cmp_le_i32_e32 vcc, v16, v184
	v_add_u32_e32 v16, 0x7d3, v2
	s_nop 0
	v_cndmask_b32_e32 v108, v217, v108, vcc
	v_cmp_le_i32_e32 vcc, v16, v184
	v_add_u32_e32 v16, 0x7f3, v2
	s_nop 0
	v_cndmask_b32_e32 v93, v217, v93, vcc
	v_cmp_le_i32_e32 vcc, v16, v184
	v_add_u32_e32 v16, 0x7d8, v2
	s_nop 0
	v_cndmask_b32_e32 v109, v217, v109, vcc
	v_cmp_le_i32_e32 vcc, v16, v184
	v_add_u32_e32 v16, 0x7f8, v2
	s_nop 0
	v_cndmask_b32_e32 v94, v217, v94, vcc
	v_cmp_le_i32_e32 vcc, v16, v184
	v_add_u32_e32 v16, 0x7d9, v2
	s_nop 0
	v_cndmask_b32_e32 v110, v217, v110, vcc
	v_cmp_le_i32_e32 vcc, v16, v184
	v_add_u32_e32 v16, 0x7f9, v2
	s_nop 0
	v_cndmask_b32_e32 v95, v217, v95, vcc
	v_cmp_le_i32_e32 vcc, v16, v184
	v_add_u32_e32 v16, 0x7da, v2
	s_nop 0
	v_cndmask_b32_e32 v111, v217, v111, vcc
	v_cmp_le_i32_e32 vcc, v16, v184
	v_add_u32_e32 v16, 0x7fa, v2
	s_nop 0
	v_cndmask_b32_e32 v96, v217, v96, vcc
	v_cmp_le_i32_e32 vcc, v16, v184
	v_add_u32_e32 v16, 0x7db, v2
	v_add_u32_e32 v2, 0x7fb, v2
	v_cndmask_b32_e32 v112, v217, v112, vcc
	v_cmp_le_i32_e32 vcc, v16, v184
	s_nop 1
	v_cndmask_b32_e32 v97, v217, v97, vcc
	v_cmp_le_i32_e32 vcc, v2, v184
	s_nop 1
	v_cndmask_b32_e32 v113, v217, v113, vcc
	s_branch .LBB0_535
.Lmy_nfA:
	s_nop 8
	v_max_f32_e32 v2, v99, v99
	v_max_f32_e32 v16, v83, v83
	v_max_f32_e32 v2, v16, v2
	v_max_f32_e32 v16, v100, v100
	v_max_f32_e32 v17, v84, v84
	v_max_f32_e32 v16, v17, v16
	v_max_f32_e32 v17, v101, v101
	v_max_f32_e32 v223, v85, v85
	v_max3_f32 v2, v82, v98, v2
	v_max_f32_e32 v17, v223, v17
	v_max3_f32 v2, v2, v16, v17
	v_max_f32_e32 v16, v102, v102
	v_max_f32_e32 v17, v86, v86
	v_max_f32_e32 v16, v17, v16
	v_max_f32_e32 v17, v103, v103
	v_max_f32_e32 v223, v87, v87
	v_max_f32_e32 v17, v223, v17
	v_max3_f32 v2, v2, v16, v17
	v_max_f32_e32 v16, v104, v104
	v_max_f32_e32 v17, v88, v88
	v_max_f32_e32 v16, v17, v16
	v_max_f32_e32 v17, v105, v105
	v_max_f32_e32 v223, v89, v89
	v_max_f32_e32 v17, v223, v17
	v_max3_f32 v2, v2, v16, v17
	v_max_f32_e32 v16, v106, v106
	v_max_f32_e32 v17, v90, v90
	v_max_f32_e32 v16, v17, v16
	v_max_f32_e32 v17, v107, v107
	v_max_f32_e32 v223, v91, v91
	v_max_f32_e32 v17, v223, v17
	v_max3_f32 v2, v2, v16, v17
	v_max_f32_e32 v16, v108, v108
	v_max_f32_e32 v17, v92, v92
	v_max_f32_e32 v16, v17, v16
	v_max_f32_e32 v17, v109, v109
	v_max_f32_e32 v223, v93, v93
	v_max_f32_e32 v17, v223, v17
	v_max3_f32 v2, v2, v16, v17
	v_max_f32_e32 v16, v110, v110
	v_max_f32_e32 v17, v94, v94
	v_max_f32_e32 v16, v17, v16
	v_max_f32_e32 v17, v111, v111
	v_max_f32_e32 v223, v95, v95
	v_max_f32_e32 v17, v223, v17
	v_max3_f32 v2, v2, v16, v17
	v_max_f32_e32 v16, v112, v112
	v_max_f32_e32 v17, v96, v96
	v_max_f32_e32 v16, v17, v16
	v_max_f32_e32 v17, v113, v113
	v_max_f32_e32 v223, v97, v97
	v_max_f32_e32 v17, v223, v17
	v_max3_f32 v2, v2, v16, v17
	v_mov_b32_e32 v16, v2
	s_nop 1
	v_permlane32_swap_b32_e32 v2, v16
	v_max_f32_e32 v16, v16, v16
	v_max_f32_e32 v2, v2, v2
	s_xor_b64 s[56:57], s[58:59], -1
	v_max_f32_e32 v2, v2, v16
	s_andn2_b64 vcc, exec, s[56:57]
	s_mov_b64 s[56:57], s[58:59]
	s_cbranch_vccnz .LBB0_538
	v_cmp_lt_f32_e32 vcc, s18, v2
	s_cmp_lg_u64 vcc, 0
	s_cselect_b64 s[56:57], -1, 0
.LBB0_538:
	s_andn2_b64 vcc, exec, s[56:57]
	s_cbranch_vccnz .LBB0_540
	v_max_f32_e32 v16, v2, v2
	v_max_f32_e32 v16, 0, v16
	v_cndmask_b32_e64 v16, v16, v2, s[58:59]
	v_exp_f32_e64 v2, -v16
	v_add_f32_e32 v185, v185, v16
	v_sub_f32_e32 v97, v97, v16
	v_sub_f32_e32 v96, v96, v16
	v_pk_mul_f32 v[80:81], v[80:81], v[2:3] op_sel_hi:[1,0]
	v_pk_mul_f32 v[78:79], v[78:79], v[2:3] op_sel_hi:[1,0]
	v_pk_mul_f32 v[76:77], v[76:77], v[2:3] op_sel_hi:[1,0]
	v_pk_mul_f32 v[74:75], v[74:75], v[2:3] op_sel_hi:[1,0]
	v_pk_mul_f32 v[72:73], v[72:73], v[2:3] op_sel_hi:[1,0]
	v_pk_mul_f32 v[70:71], v[70:71], v[2:3] op_sel_hi:[1,0]
	v_pk_mul_f32 v[68:69], v[68:69], v[2:3] op_sel_hi:[1,0]
	v_pk_mul_f32 v[66:67], v[66:67], v[2:3] op_sel_hi:[1,0]
	v_pk_mul_f32 v[64:65], v[64:65], v[2:3] op_sel_hi:[1,0]
	v_pk_mul_f32 v[62:63], v[62:63], v[2:3] op_sel_hi:[1,0]
	v_pk_mul_f32 v[60:61], v[60:61], v[2:3] op_sel_hi:[1,0]
	v_pk_mul_f32 v[58:59], v[58:59], v[2:3] op_sel_hi:[1,0]
	v_pk_mul_f32 v[56:57], v[56:57], v[2:3] op_sel_hi:[1,0]
	v_pk_mul_f32 v[54:55], v[54:55], v[2:3] op_sel_hi:[1,0]
	v_pk_mul_f32 v[52:53], v[52:53], v[2:3] op_sel_hi:[1,0]
	v_pk_mul_f32 v[50:51], v[50:51], v[2:3] op_sel_hi:[1,0]
	v_pk_mul_f32 v[48:49], v[48:49], v[2:3] op_sel_hi:[1,0]
	v_pk_mul_f32 v[46:47], v[46:47], v[2:3] op_sel_hi:[1,0]
	v_pk_mul_f32 v[44:45], v[44:45], v[2:3] op_sel_hi:[1,0]
	v_pk_mul_f32 v[42:43], v[42:43], v[2:3] op_sel_hi:[1,0]
	v_pk_mul_f32 v[40:41], v[40:41], v[2:3] op_sel_hi:[1,0]
	v_pk_mul_f32 v[38:39], v[38:39], v[2:3] op_sel_hi:[1,0]
	v_pk_mul_f32 v[36:37], v[36:37], v[2:3] op_sel_hi:[1,0]
	v_pk_mul_f32 v[34:35], v[34:35], v[2:3] op_sel_hi:[1,0]
	v_pk_mul_f32 v[32:33], v[32:33], v[2:3] op_sel_hi:[1,0]
	v_pk_mul_f32 v[30:31], v[30:31], v[2:3] op_sel_hi:[1,0]
	v_pk_mul_f32 v[28:29], v[28:29], v[2:3] op_sel_hi:[1,0]
	v_pk_mul_f32 v[26:27], v[26:27], v[2:3] op_sel_hi:[1,0]
	v_pk_mul_f32 v[24:25], v[24:25], v[2:3] op_sel_hi:[1,0]
	v_pk_mul_f32 v[22:23], v[22:23], v[2:3] op_sel_hi:[1,0]
	v_pk_mul_f32 v[20:21], v[20:21], v[2:3] op_sel_hi:[1,0]
	v_pk_mul_f32 v[18:19], v[18:19], v[2:3] op_sel_hi:[1,0]
	v_mul_f32_e32 v168, v168, v2
	v_sub_f32_e32 v95, v95, v16
	v_sub_f32_e32 v94, v94, v16
	v_sub_f32_e32 v93, v93, v16
	v_sub_f32_e32 v92, v92, v16
	v_sub_f32_e32 v91, v91, v16
	v_sub_f32_e32 v90, v90, v16
	v_sub_f32_e32 v89, v89, v16
	v_sub_f32_e32 v88, v88, v16
	v_sub_f32_e32 v87, v87, v16
	v_sub_f32_e32 v86, v86, v16
	v_sub_f32_e32 v85, v85, v16
	v_sub_f32_e32 v84, v84, v16
	v_sub_f32_e32 v83, v83, v16
	v_sub_f32_e32 v82, v82, v16
	v_sub_f32_e32 v113, v113, v16
	v_sub_f32_e32 v112, v112, v16
	v_sub_f32_e32 v111, v111, v16
	v_sub_f32_e32 v110, v110, v16
	v_sub_f32_e32 v109, v109, v16
	v_sub_f32_e32 v108, v108, v16
	v_sub_f32_e32 v107, v107, v16
	v_sub_f32_e32 v106, v106, v16
	v_sub_f32_e32 v105, v105, v16
	v_sub_f32_e32 v104, v104, v16
	v_sub_f32_e32 v103, v103, v16
	v_sub_f32_e32 v102, v102, v16
	v_sub_f32_e32 v101, v101, v16
	v_sub_f32_e32 v100, v100, v16
	v_sub_f32_e32 v99, v99, v16
	v_sub_f32_e32 v98, v98, v16
	s_branch .LBB0_540
.Lmy_maskB:
	v_add_u32_e32 v2, s84, v222
	v_add_u32_e32 v17, 0x7a0, v2
	v_add_u32_e32 v16, 0x780, v2
	v_cmp_le_i32_e32 vcc, v17, v184
	s_nop 6
	v_cndmask_b32_e32 v98, v217, v98, vcc
	v_cmp_lt_i32_e32 vcc, v16, v184
	s_nop 1
	v_cndmask_b32_e32 v83, v217, v83, vcc
	v_cmp_le_i32_e32 vcc, v16, v184
	v_add_u32_e32 v16, 0x7a1, v2
	s_nop 0
	v_cndmask_b32_e32 v82, v217, v82, vcc
	v_cmp_le_i32_e32 vcc, v16, v184
	v_add_u32_e32 v16, 0x782, v2
	s_nop 0
	v_cndmask_b32_e32 v99, v217, v99, vcc
	v_cmp_le_i32_e32 vcc, v16, v184
	v_add_u32_e32 v16, 0x7a2, v2
	s_nop 0
	v_cndmask_b32_e32 v84, v217, v84, vcc
	v_cmp_le_i32_e32 vcc, v16, v184
	v_add_u32_e32 v16, 0x783, v2
	s_nop 0
	v_cndmask_b32_e32 v100, v217, v100, vcc
	v_cmp_le_i32_e32 vcc, v16, v184
	v_add_u32_e32 v16, 0x7a3, v2
	s_nop 0
	v_cndmask_b32_e32 v85, v217, v85, vcc
	v_cmp_le_i32_e32 vcc, v16, v184
	v_add_u32_e32 v16, 0x788, v2
	s_nop 0
	v_cndmask_b32_e32 v101, v217, v101, vcc
	v_cmp_le_i32_e32 vcc, v16, v184
	v_add_u32_e32 v16, 0x7a8, v2
	s_nop 0
	v_cndmask_b32_e32 v86, v217, v86, vcc
	v_cmp_le_i32_e32 vcc, v16, v184
	v_add_u32_e32 v16, 0x789, v2
	s_nop 0
	v_cndmask_b32_e32 v102, v217, v102, vcc
	v_cmp_le_i32_e32 vcc, v16, v184
	v_add_u32_e32 v16, 0x7a9, v2
	s_nop 0
	v_cndmask_b32_e32 v87, v217, v87, vcc
	v_cmp_le_i32_e32 vcc, v16, v184
	v_add_u32_e32 v16, 0x78a, v2
	s_nop 0
	v_cndmask_b32_e32 v103, v217, v103, vcc
	v_cmp_le_i32_e32 vcc, v16, v184
	v_add_u32_e32 v16, 0x7aa, v2
	s_nop 0
	v_cndmask_b32_e32 v88, v217, v88, vcc
	v_cmp_le_i32_e32 vcc, v16, v184
	v_add_u32_e32 v16, 0x78b, v2
	s_nop 0
	v_cndmask_b32_e32 v104, v217, v104, vcc
	v_cmp_le_i32_e32 vcc, v16, v184
	v_add_u32_e32 v16, 0x7ab, v2
	s_nop 0
	v_cndmask_b32_e32 v89, v217, v89, vcc
	v_cmp_le_i32_e32 vcc, v16, v184
	v_add_u32_e32 v16, 0x790, v2
	s_nop 0
	v_cndmask_b32_e32 v105, v217, v105, vcc
	v_cmp_le_i32_e32 vcc, v16, v184
	v_add_u32_e32 v16, 0x7b0, v2
	s_nop 0
	v_cndmask_b32_e32 v90, v217, v90, vcc
	v_cmp_le_i32_e32 vcc, v16, v184
	v_add_u32_e32 v16, 0x791, v2
	s_nop 0
	v_cndmask_b32_e32 v106, v217, v106, vcc
	v_cmp_le_i32_e32 vcc, v16, v184
	v_add_u32_e32 v16, 0x7b1, v2
	s_nop 0
	v_cndmask_b32_e32 v91, v217, v91, vcc
	v_cmp_le_i32_e32 vcc, v16, v184
	v_add_u32_e32 v16, 0x792, v2
	s_nop 0
	v_cndmask_b32_e32 v107, v217, v107, vcc
	v_cmp_le_i32_e32 vcc, v16, v184
	v_add_u32_e32 v16, 0x7b2, v2
	s_nop 0
	v_cndmask_b32_e32 v92, v217, v92, vcc
	v_cmp_le_i32_e32 vcc, v16, v184
	v_add_u32_e32 v16, 0x793, v2
	s_nop 0
	v_cndmask_b32_e32 v108, v217, v108, vcc
	v_cmp_le_i32_e32 vcc, v16, v184
	v_add_u32_e32 v16, 0x7b3, v2
	s_nop 0
	v_cndmask_b32_e32 v93, v217, v93, vcc
	v_cmp_le_i32_e32 vcc, v16, v184
	v_add_u32_e32 v16, 0x798, v2
	s_nop 0
	v_cndmask_b32_e32 v109, v217, v109, vcc
	v_cmp_le_i32_e32 vcc, v16, v184
	v_add_u32_e32 v16, 0x7b8, v2
	s_nop 0
	v_cndmask_b32_e32 v94, v217, v94, vcc
	v_cmp_le_i32_e32 vcc, v16, v184
	v_add_u32_e32 v16, 0x799, v2
	s_nop 0
	v_cndmask_b32_e32 v110, v217, v110, vcc
	v_cmp_le_i32_e32 vcc, v16, v184
	v_add_u32_e32 v16, 0x7b9, v2
	s_nop 0
	v_cndmask_b32_e32 v95, v217, v95, vcc
	v_cmp_le_i32_e32 vcc, v16, v184
	v_add_u32_e32 v16, 0x79a, v2
	s_nop 0
	v_cndmask_b32_e32 v111, v217, v111, vcc
	v_cmp_le_i32_e32 vcc, v16, v184
	v_add_u32_e32 v16, 0x7ba, v2
	s_nop 0
	v_cndmask_b32_e32 v96, v217, v96, vcc
	v_cmp_le_i32_e32 vcc, v16, v184
	v_add_u32_e32 v16, 0x79b, v2
	v_add_u32_e32 v2, 0x7bb, v2
	v_cndmask_b32_e32 v112, v217, v112, vcc
	v_cmp_le_i32_e32 vcc, v16, v184
	s_nop 1
	v_cndmask_b32_e32 v97, v217, v97, vcc
	v_cmp_le_i32_e32 vcc, v2, v184
	s_nop 1
	v_cndmask_b32_e32 v113, v217, v113, vcc
	s_branch .LBB0_551
.Lmy_nfB:
	s_nop 8
	v_max_f32_e32 v2, v99, v99
	v_max_f32_e32 v16, v83, v83
	v_max_f32_e32 v2, v16, v2
	v_max_f32_e32 v16, v100, v100
	v_max_f32_e32 v17, v84, v84
	v_max_f32_e32 v16, v17, v16
	v_max_f32_e32 v17, v101, v101
	v_max_f32_e32 v223, v85, v85
	v_max3_f32 v2, v82, v98, v2
	v_max_f32_e32 v17, v223, v17
	v_max3_f32 v2, v2, v16, v17
	v_max_f32_e32 v16, v102, v102
	v_max_f32_e32 v17, v86, v86
	v_max_f32_e32 v16, v17, v16
	v_max_f32_e32 v17, v103, v103
	v_max_f32_e32 v223, v87, v87
	v_max_f32_e32 v17, v223, v17
	v_max3_f32 v2, v2, v16, v17
	v_max_f32_e32 v16, v104, v104
	v_max_f32_e32 v17, v88, v88
	v_max_f32_e32 v16, v17, v16
	v_max_f32_e32 v17, v105, v105
	v_max_f32_e32 v223, v89, v89
	v_max_f32_e32 v17, v223, v17
	v_max3_f32 v2, v2, v16, v17
	v_max_f32_e32 v16, v106, v106
	v_max_f32_e32 v17, v90, v90
	v_max_f32_e32 v16, v17, v16
	v_max_f32_e32 v17, v107, v107
	v_max_f32_e32 v223, v91, v91
	v_max_f32_e32 v17, v223, v17
	v_max3_f32 v2, v2, v16, v17
	v_max_f32_e32 v16, v108, v108
	v_max_f32_e32 v17, v92, v92
	v_max_f32_e32 v16, v17, v16
	v_max_f32_e32 v17, v109, v109
	v_max_f32_e32 v223, v93, v93
	v_max_f32_e32 v17, v223, v17
	v_max3_f32 v2, v2, v16, v17
	v_max_f32_e32 v16, v110, v110
	v_max_f32_e32 v17, v94, v94
	v_max_f32_e32 v16, v17, v16
	v_max_f32_e32 v17, v111, v111
	v_max_f32_e32 v223, v95, v95
	v_max_f32_e32 v17, v223, v17
	v_max3_f32 v2, v2, v16, v17
	v_max_f32_e32 v16, v112, v112
	v_max_f32_e32 v17, v96, v96
	v_max_f32_e32 v16, v17, v16
	v_max_f32_e32 v17, v113, v113
	v_max_f32_e32 v223, v97, v97
	v_max_f32_e32 v17, v223, v17
	v_max3_f32 v2, v2, v16, v17
	v_mov_b32_e32 v16, v2
	s_nop 1
	v_permlane32_swap_b32_e32 v2, v16
	v_max_f32_e32 v16, v16, v16
	v_max_f32_e32 v2, v2, v2
	s_xor_b64 s[60:61], s[58:59], -1
	v_max_f32_e32 v2, v2, v16
	s_andn2_b64 vcc, exec, s[60:61]
	s_mov_b64 s[60:61], s[58:59]
	s_cbranch_vccnz .LBB0_554
	v_cmp_lt_f32_e32 vcc, s18, v2
	s_cmp_lg_u64 vcc, 0
	s_cselect_b64 s[60:61], -1, 0
.LBB0_554:
	s_andn2_b64 vcc, exec, s[60:61]
	s_cbranch_vccnz .LBB0_556
	v_max_f32_e32 v16, v2, v2
	v_max_f32_e32 v16, 0, v16
	v_cndmask_b32_e64 v16, v16, v2, s[58:59]
	v_exp_f32_e64 v2, -v16
	v_add_f32_e32 v185, v185, v16
	v_sub_f32_e32 v97, v97, v16
	v_sub_f32_e32 v96, v96, v16
	v_pk_mul_f32 v[80:81], v[80:81], v[2:3] op_sel_hi:[1,0]
	v_pk_mul_f32 v[78:79], v[78:79], v[2:3] op_sel_hi:[1,0]
	v_pk_mul_f32 v[76:77], v[76:77], v[2:3] op_sel_hi:[1,0]
	v_pk_mul_f32 v[74:75], v[74:75], v[2:3] op_sel_hi:[1,0]
	v_pk_mul_f32 v[72:73], v[72:73], v[2:3] op_sel_hi:[1,0]
	v_pk_mul_f32 v[70:71], v[70:71], v[2:3] op_sel_hi:[1,0]
	v_pk_mul_f32 v[68:69], v[68:69], v[2:3] op_sel_hi:[1,0]
	v_pk_mul_f32 v[66:67], v[66:67], v[2:3] op_sel_hi:[1,0]
	v_pk_mul_f32 v[64:65], v[64:65], v[2:3] op_sel_hi:[1,0]
	v_pk_mul_f32 v[62:63], v[62:63], v[2:3] op_sel_hi:[1,0]
	v_pk_mul_f32 v[60:61], v[60:61], v[2:3] op_sel_hi:[1,0]
	v_pk_mul_f32 v[58:59], v[58:59], v[2:3] op_sel_hi:[1,0]
	v_pk_mul_f32 v[56:57], v[56:57], v[2:3] op_sel_hi:[1,0]
	v_pk_mul_f32 v[54:55], v[54:55], v[2:3] op_sel_hi:[1,0]
	v_pk_mul_f32 v[52:53], v[52:53], v[2:3] op_sel_hi:[1,0]
	v_pk_mul_f32 v[50:51], v[50:51], v[2:3] op_sel_hi:[1,0]
	v_pk_mul_f32 v[48:49], v[48:49], v[2:3] op_sel_hi:[1,0]
	v_pk_mul_f32 v[46:47], v[46:47], v[2:3] op_sel_hi:[1,0]
	v_pk_mul_f32 v[44:45], v[44:45], v[2:3] op_sel_hi:[1,0]
	v_pk_mul_f32 v[42:43], v[42:43], v[2:3] op_sel_hi:[1,0]
	v_pk_mul_f32 v[40:41], v[40:41], v[2:3] op_sel_hi:[1,0]
	v_pk_mul_f32 v[38:39], v[38:39], v[2:3] op_sel_hi:[1,0]
	v_pk_mul_f32 v[36:37], v[36:37], v[2:3] op_sel_hi:[1,0]
	v_pk_mul_f32 v[34:35], v[34:35], v[2:3] op_sel_hi:[1,0]
	v_pk_mul_f32 v[32:33], v[32:33], v[2:3] op_sel_hi:[1,0]
	v_pk_mul_f32 v[30:31], v[30:31], v[2:3] op_sel_hi:[1,0]
	v_pk_mul_f32 v[28:29], v[28:29], v[2:3] op_sel_hi:[1,0]
	v_pk_mul_f32 v[26:27], v[26:27], v[2:3] op_sel_hi:[1,0]
	v_pk_mul_f32 v[24:25], v[24:25], v[2:3] op_sel_hi:[1,0]
	v_pk_mul_f32 v[22:23], v[22:23], v[2:3] op_sel_hi:[1,0]
	v_pk_mul_f32 v[20:21], v[20:21], v[2:3] op_sel_hi:[1,0]
	v_pk_mul_f32 v[18:19], v[18:19], v[2:3] op_sel_hi:[1,0]
	v_mul_f32_e32 v168, v168, v2
	v_sub_f32_e32 v95, v95, v16
	v_sub_f32_e32 v94, v94, v16
	v_sub_f32_e32 v93, v93, v16
	v_sub_f32_e32 v92, v92, v16
	v_sub_f32_e32 v91, v91, v16
	v_sub_f32_e32 v90, v90, v16
	v_sub_f32_e32 v89, v89, v16
	v_sub_f32_e32 v88, v88, v16
	v_sub_f32_e32 v87, v87, v16
	v_sub_f32_e32 v86, v86, v16
	v_sub_f32_e32 v85, v85, v16
	v_sub_f32_e32 v84, v84, v16
	v_sub_f32_e32 v83, v83, v16
	v_sub_f32_e32 v82, v82, v16
	v_sub_f32_e32 v113, v113, v16
	v_sub_f32_e32 v112, v112, v16
	v_sub_f32_e32 v111, v111, v16
	v_sub_f32_e32 v110, v110, v16
	v_sub_f32_e32 v109, v109, v16
	v_sub_f32_e32 v108, v108, v16
	v_sub_f32_e32 v107, v107, v16
	v_sub_f32_e32 v106, v106, v16
	v_sub_f32_e32 v105, v105, v16
	v_sub_f32_e32 v104, v104, v16
	v_sub_f32_e32 v103, v103, v16
	v_sub_f32_e32 v102, v102, v16
	v_sub_f32_e32 v101, v101, v16
	v_sub_f32_e32 v100, v100, v16
	v_sub_f32_e32 v99, v99, v16
	v_sub_f32_e32 v98, v98, v16
	s_branch .LBB0_556
